# attention softmax: no-rescale decision taken from lane-local tile maxima first; the cross-lane row-max exchange (ds_bpermute + wait) only runs when some lane exceeds the threshold
# speedup vs baseline: 1.0110x; 1.0091x over previous
.LBB0_961:
	s_bitcmp1_b32 s35, 0
	s_cselect_b32 s35, 0xac00, 0
	s_add_i32 s35, s35, 0
	v_add3_u32 v1, s35, v209, v204
	ds_read_b128 v[2:5], v1
	ds_read_b128 v[6:9], v1 offset:32
	ds_read_b128 v[10:13], v1 offset:12800
	ds_read_b128 v[96:99], v1 offset:12832
	v_add_u32_e32 v14, s35, v210
	ds_read_b128 v[180:183], v1 offset:64
	ds_read_b128 v[216:219], v1 offset:96
	ds_read_b128 v[220:223], v1 offset:12864
	ds_read_b128 v[224:227], v1 offset:12896
	s_waitcnt lgkmcnt(5)
	v_mfma_f32_32x32x16_bf16 v[80:95], v[10:13], v[132:135], 0
	s_waitcnt lgkmcnt(4)
	v_mfma_f32_32x32x16_bf16 v[80:95], v[96:99], v[136:139], v[80:95]
	v_mfma_f32_32x32x16_bf16 v[96:111], v[2:5], v[132:135], 0
	ds_read_b128 v[2:5], v1 offset:128
	ds_read_b128 v[10:13], v1 offset:160
	ds_read_b128 v[228:231], v1 offset:12928
	ds_read_b128 v[232:235], v1 offset:12960
	v_mfma_f32_32x32x16_bf16 v[96:111], v[6:9], v[136:139], v[96:111]
	s_waitcnt lgkmcnt(7)
	v_mfma_f32_32x32x16_bf16 v[96:111], v[180:183], v[140:143], v[96:111]
	s_waitcnt lgkmcnt(5)
	v_mfma_f32_32x32x16_bf16 v[80:95], v[220:223], v[140:143], v[80:95]
	v_mfma_f32_32x32x16_bf16 v[96:111], v[216:219], v[144:147], v[96:111]
	ds_read_b128 v[6:9], v1 offset:192
	ds_read_b128 v[180:183], v1 offset:224
	ds_read_b128 v[216:219], v1 offset:12992
	ds_read_b128 v[220:223], v1 offset:13024
	s_waitcnt lgkmcnt(8)
	v_mfma_f32_32x32x16_bf16 v[80:95], v[224:227], v[144:147], v[80:95]
	s_waitcnt lgkmcnt(7)
	v_mfma_f32_32x32x16_bf16 v[96:111], v[2:5], v[148:151], v[96:111]
	s_waitcnt lgkmcnt(5)
	v_mfma_f32_32x32x16_bf16 v[80:95], v[228:231], v[148:151], v[80:95]
	v_mfma_f32_32x32x16_bf16 v[96:111], v[10:13], v[152:155], v[96:111]
	ds_read_b128 v[2:5], v1 offset:256
	ds_read_b128 v[10:13], v1 offset:288
	ds_read_b128 v[224:227], v1 offset:13056
	ds_read_b128 v[228:231], v1 offset:13088
	s_waitcnt lgkmcnt(8)
	v_mfma_f32_32x32x16_bf16 v[80:95], v[232:235], v[152:155], v[80:95]
	s_waitcnt lgkmcnt(7)
	v_mfma_f32_32x32x16_bf16 v[96:111], v[6:9], v[156:159], v[96:111]
	s_waitcnt lgkmcnt(5)
	v_mfma_f32_32x32x16_bf16 v[80:95], v[216:219], v[156:159], v[80:95]
	ds_read_b128 v[216:219], v1 offset:320
	ds_read_b128 v[232:235], v1 offset:352
	ds_read_b128 v[236:239], v1 offset:13120
	ds_read_b128 v[240:243], v1 offset:13152
	v_mfma_f32_32x32x16_bf16 v[96:111], v[180:183], v[160:163], v[96:111]
	s_waitcnt lgkmcnt(8)
	v_mfma_f32_32x32x16_bf16 v[80:95], v[220:223], v[160:163], v[80:95]
	v_add_u32_e32 v1, v14, v204
	s_waitcnt lgkmcnt(7)
	v_mfma_f32_32x32x16_bf16 v[96:111], v[2:5], v[164:167], v[96:111]
	s_waitcnt lgkmcnt(5)
	v_mfma_f32_32x32x16_bf16 v[80:95], v[224:227], v[164:167], v[80:95]
	v_mfma_f32_32x32x16_bf16 v[96:111], v[10:13], v[168:171], v[96:111]
	ds_read_b128 v[180:183], v1 offset:25600
	ds_read_b128 v[10:13], v1 offset:25632
	ds_read_b128 v[6:9], v1 offset:25664
	ds_read_b128 v[2:5], v1 offset:25696
	s_waitcnt lgkmcnt(8)
	v_mfma_f32_32x32x16_bf16 v[80:95], v[228:231], v[168:171], v[80:95]
	s_waitcnt lgkmcnt(7)
	v_mfma_f32_32x32x16_bf16 v[96:111], v[216:219], v[172:175], v[96:111]
	s_waitcnt lgkmcnt(5)
	v_mfma_f32_32x32x16_bf16 v[80:95], v[236:239], v[172:175], v[80:95]
	v_mfma_f32_32x32x16_bf16 v[96:111], v[232:235], v[176:179], v[96:111]
	s_waitcnt lgkmcnt(4)
	v_mfma_f32_32x32x16_bf16 v[80:95], v[240:243], v[176:179], v[80:95]
	s_nop 15
	s_nop 3
	s_nop 0
	v_max3_f32 v14, v96, v97, v98
	v_max3_f32 v215, v99, v100, v101
	v_max3_f32 v15, v80, v81, v82
	v_max3_f32 v216, v83, v84, v85
	v_max3_f32 v217, v102, v103, v104
	v_max3_f32 v218, v86, v87, v88
	v_max3_f32 v220, v89, v90, v91
	v_max3_f32 v219, v105, v106, v107
	v_max3_f32 v221, v108, v109, v110
	v_max3_f32 v222, v92, v93, v94
	s_nop 0
	v_max3_f32 v14, v14, v215, v217
	v_max3_f32 v215, v216, v218, v220
	v_max3_f32 v15, v219, v221, v15
	v_max3_f32 v216, v222, v111, v95
	s_nop 0
	v_max3_f32 v14, v14, v15, v215
	v_and_b32_e32 v215, 64, v212
	v_xor_b32_e32 v15, 32, v212
	v_add_u32_e32 v215, 64, v215
	v_cmp_lt_i32_e32 vcc, v15, v215
	v_max3_f32 v14, v14, v216, v216
	v_sub_f32_e32 v216, v14, v214
	v_cmp_ge_f32_e64 s[98:99], s43, v216
	s_cmp_eq_u64 s[98:99], exec
	s_cbranch_scc1 .Lattn_nobp
	s_nop 1
	v_cndmask_b32_e32 v15, v212, v15, vcc
	v_lshlrev_b32_e32 v15, 2, v15
	ds_bpermute_b32 v15, v15, v14
	v_max_f32_e32 v14, v14, v14
	s_waitcnt lgkmcnt(0)
	v_max_f32_e32 v15, v15, v15
	v_max_f32_e32 v14, v14, v15
	v_sub_f32_e32 v15, v14, v214
	v_cmp_ge_f32_e32 vcc, s43, v15
	s_cmp_eq_u64 vcc, exec
	s_cbranch_scc1 .LBB0_963
	v_max_f32_e32 v14, v14, v14
	v_max_f32_e32 v15, v214, v214
	v_max_f32_e32 v15, v15, v14
	v_sub_f32_e32 v14, v214, v15
	v_exp_f32_e32 v14, v14
	v_mov_b32_e32 v214, v15
	v_pk_mul_f32 v[78:79], v[78:79], v[14:15] op_sel_hi:[1,0]
	v_pk_mul_f32 v[76:77], v[76:77], v[14:15] op_sel_hi:[1,0]
	v_pk_mul_f32 v[74:75], v[74:75], v[14:15] op_sel_hi:[1,0]
	v_pk_mul_f32 v[72:73], v[72:73], v[14:15] op_sel_hi:[1,0]
	v_pk_mul_f32 v[70:71], v[70:71], v[14:15] op_sel_hi:[1,0]
	v_pk_mul_f32 v[68:69], v[68:69], v[14:15] op_sel_hi:[1,0]
	v_pk_mul_f32 v[66:67], v[66:67], v[14:15] op_sel_hi:[1,0]
	v_pk_mul_f32 v[64:65], v[64:65], v[14:15] op_sel_hi:[1,0]
	v_pk_mul_f32 v[62:63], v[62:63], v[14:15] op_sel_hi:[1,0]
	v_pk_mul_f32 v[60:61], v[60:61], v[14:15] op_sel_hi:[1,0]
	v_pk_mul_f32 v[58:59], v[58:59], v[14:15] op_sel_hi:[1,0]
	v_pk_mul_f32 v[56:57], v[56:57], v[14:15] op_sel_hi:[1,0]
	v_pk_mul_f32 v[54:55], v[54:55], v[14:15] op_sel_hi:[1,0]
	v_pk_mul_f32 v[52:53], v[52:53], v[14:15] op_sel_hi:[1,0]
	v_pk_mul_f32 v[50:51], v[50:51], v[14:15] op_sel_hi:[1,0]
	v_pk_mul_f32 v[48:49], v[48:49], v[14:15] op_sel_hi:[1,0]
	v_pk_mul_f32 v[46:47], v[46:47], v[14:15] op_sel_hi:[1,0]
	v_pk_mul_f32 v[44:45], v[44:45], v[14:15] op_sel_hi:[1,0]
	v_pk_mul_f32 v[42:43], v[42:43], v[14:15] op_sel_hi:[1,0]
	v_pk_mul_f32 v[40:41], v[40:41], v[14:15] op_sel_hi:[1,0]
	v_pk_mul_f32 v[38:39], v[38:39], v[14:15] op_sel_hi:[1,0]
	v_pk_mul_f32 v[36:37], v[36:37], v[14:15] op_sel_hi:[1,0]
	v_pk_mul_f32 v[34:35], v[34:35], v[14:15] op_sel_hi:[1,0]
	v_pk_mul_f32 v[32:33], v[32:33], v[14:15] op_sel_hi:[1,0]
	v_pk_mul_f32 v[30:31], v[30:31], v[14:15] op_sel_hi:[1,0]
	v_pk_mul_f32 v[28:29], v[28:29], v[14:15] op_sel_hi:[1,0]
	v_pk_mul_f32 v[26:27], v[26:27], v[14:15] op_sel_hi:[1,0]
	v_pk_mul_f32 v[24:25], v[24:25], v[14:15] op_sel_hi:[1,0]
	v_pk_mul_f32 v[22:23], v[22:23], v[14:15] op_sel_hi:[1,0]
	v_pk_mul_f32 v[20:21], v[20:21], v[14:15] op_sel_hi:[1,0]
	v_pk_mul_f32 v[18:19], v[18:19], v[14:15] op_sel_hi:[1,0]
	v_pk_mul_f32 v[16:17], v[16:17], v[14:15] op_sel_hi:[1,0]
	v_mul_f32_e32 v213, v213, v14

.Lattn_nobp:
	s_waitcnt lgkmcnt(0)
	s_branch .LBB0_963
